# conv_tile staging: zero-fill of out-of-sequence rows moved after the load wait (robust against stale in-flight loads)
# baseline (speedup 1.0000x reference)
; DEV void conv_tile(const Params& p, int tile, char* smem) {
;     ...
;   __syncthreads();
;   for (int id = tid; id < 38 * 64; id += 256) {
;     const int row = id >> 6, cc = id & 63;
;     const int t = t0 - 15 + row;
;     uint4 v = make_uint4(0u, 0u, 0u, 0u);
;     if (t >= 0 && t < seq_len) v = *(const uint4*)(YG + (size_t)(seq_start + t) * 512 + cc * 8);
;     *(uint4*)(stg + row * 512 + cc * 8) = v;
.LBB0_781:
	s_cmpk_gt_i32 s16, 0x317
	s_mov_b64 s[6:7], -1
	s_cbranch_scc0 .LBB0_788
	s_cmpk_gt_u32 s16, 0x737
	s_cbranch_scc0 .LBB0_794
	s_add_i32 s6, s16, 0xfffff8c8
	s_and_b32 s7, s16, 7
	s_mul_i32 s17, s7, 0x108
	s_lshr_b32 s6, s6, 3
	s_add_i32 s17, s17, s6
	v_mov_b32_e32 v74, v195
	s_movk_i32 s6, 0x980
	s_movk_i32 s12, 0x2000
	s_waitcnt lgkmcnt(0)
	v_and_b32_e32 v70, 63, v74
	v_cmp_gt_i32_e32 vcc, s6, v74
	s_barrier
	s_and_saveexec_b64 s[6:7], vcc
	s_mov_b32 s34, 0x800000
	s_cbranch_execz .LBB0_789
	s_lshl_b32 s21, s17, 3
	s_cmpk_lt_u32 s17, 0x800
	s_movk_i32 s10, 0x7f00
	s_cselect_b32 s10, 0x2000, s10
	s_cselect_b32 s20, s12, 0x100
	s_and_b32 s10, s10, s21
	s_add_i32 s21, s21, -15
	s_sub_i32 s22, s21, s10
	v_readlane_b32 s10, v254, 8
	v_lshlrev_b32_e32 v6, 4, v70
	v_mov_b32_e32 v7, v1
	v_readlane_b32 s11, v254, 9
	s_nop 1
	v_lshl_add_u64 v[8:9], s[10:11], 0, v[6:7]
	v_lshrrev_b32_e32 v10, 6, v74
	v_add_u32_e32 v2, s21, v10
	v_ashrrev_i32_e32 v3, 31, v2
	v_readfirstlane_b32 s30, v10
	v_lshlrev_b64 v[2:3], 10, v[2:3]
	v_lshl_add_u64 v[2:3], v[8:9], 0, v[2:3]
	v_lshl_or_b32 v0, v10, 10, v6
	s_mov_b32 s38, 0x1000
	s_mov_b32 s39, 0
	s_add_i32 s31, s22, s30
	s_cmp_lt_u32 s31, s20
	s_cbranch_scc0 .Lcv_ld_skip_0
	global_load_dwordx4 v[12:15], v[2:3], off

; DEV void conv_tile(const Params& p, int tile, char* smem) {
;     ...
;     uint4 v = make_uint4(0u, 0u, 0u, 0u);
;     if (t >= 0 && t < seq_len) v = *(const uint4*)(YG + (size_t)(seq_start + t) * 512 + cc * 8);
;     *(uint4*)(stg + row * 512 + cc * 8) = v;
.Lcv_ld_skip_9:
	s_waitcnt vmcnt(0)
	s_add_i32 s31, s22, s30
	s_cmp_lt_u32 s31, s20
	s_cbranch_scc1 .Lcv_z_skip_0
	v_mov_b64_e32 v[12:13], 0
	v_mov_b64_e32 v[14:15], 0
.Lcv_z_skip_0:
	s_add_i32 s31, s31, 4
	s_cmp_lt_u32 s31, s20
	s_cbranch_scc1 .Lcv_z_skip_1
	v_mov_b64_e32 v[16:17], 0
	v_mov_b64_e32 v[18:19], 0
.Lcv_z_skip_1:
	s_add_i32 s31, s31, 4
	s_cmp_lt_u32 s31, s20
	s_cbranch_scc1 .Lcv_z_skip_2
	v_mov_b64_e32 v[20:21], 0
	v_mov_b64_e32 v[22:23], 0
.Lcv_z_skip_2:
	s_add_i32 s31, s31, 4
	s_cmp_lt_u32 s31, s20
	s_cbranch_scc1 .Lcv_z_skip_3
	v_mov_b64_e32 v[24:25], 0
	v_mov_b64_e32 v[26:27], 0
.Lcv_z_skip_3:
	s_add_i32 s31, s31, 4
	s_cmp_lt_u32 s31, s20
	s_cbranch_scc1 .Lcv_z_skip_4
	v_mov_b64_e32 v[28:29], 0
	v_mov_b64_e32 v[30:31], 0
.Lcv_z_skip_4:
	s_add_i32 s31, s31, 4
	s_cmp_lt_u32 s31, s20
	s_cbranch_scc1 .Lcv_z_skip_5
	v_mov_b64_e32 v[32:33], 0
	v_mov_b64_e32 v[34:35], 0
.Lcv_z_skip_5:
	s_add_i32 s31, s31, 4
	s_cmp_lt_u32 s31, s20
	s_cbranch_scc1 .Lcv_z_skip_6
	v_mov_b64_e32 v[36:37], 0
	v_mov_b64_e32 v[38:39], 0
.Lcv_z_skip_6:
	s_add_i32 s31, s31, 4
	s_cmp_lt_u32 s31, s20
	s_cbranch_scc1 .Lcv_z_skip_7
	v_mov_b64_e32 v[40:41], 0
	v_mov_b64_e32 v[42:43], 0
.Lcv_z_skip_7:
	s_add_i32 s31, s31, 4
	s_cmp_lt_u32 s31, s20
	s_cbranch_scc1 .Lcv_z_skip_8
	v_mov_b64_e32 v[44:45], 0
	v_mov_b64_e32 v[46:47], 0
.Lcv_z_skip_8:
	s_add_i32 s31, s31, 4
	s_cmp_lt_u32 s31, s20
	s_cbranch_scc1 .Lcv_z_skip_9
	v_mov_b64_e32 v[48:49], 0
	v_mov_b64_e32 v[50:51], 0
.Lcv_z_skip_9:
	ds_write_b128 v0, v[12:15]
	ds_write_b128 v0, v[16:19] offset:4096
	ds_write_b128 v0, v[20:23] offset:8192
	ds_write_b128 v0, v[24:27] offset:12288
	ds_write_b128 v0, v[28:31] offset:16384
	ds_write_b128 v0, v[32:35] offset:20480
	ds_write_b128 v0, v[36:39] offset:24576
	ds_write_b128 v0, v[40:43] offset:28672
	ds_write_b128 v0, v[44:47] offset:32768
	s_cmp_lt_u32 s30, 2
	s_cbranch_scc0 .LBB0_789
	ds_write_b128 v0, v[48:51] offset:36864
	s_branch .LBB0_789
